# grid barrier: acquire buffer_inv moved from exit path to arrival (overlapped with arrive atomic) in the 9 in-loop barrier copies; on top of v31
# speedup vs baseline: 1.0103x; 1.0103x over previous
; __device__ __forceinline__ unsigned xb_ld(unsigned* p)              { return __hip_atomic_load(p, __ATOMIC_RELAXED, __HIP_MEMORY_SCOPE_AGENT); }
; __device__ __forceinline__ unsigned xb_add(unsigned* p, unsigned v) { return __hip_atomic_fetch_add(p, v, __ATOMIC_RELAXED, __HIP_MEMORY_SCOPE_AGENT); }
; #define XB_SPIN(cond, bar) do { unsigned _sp = 0; while (cond) { __builtin_amdgcn_s_sleep(1); \
;     if ((++_sp & 255u) == 0u) { if (xb_ld(&(bar)[XB_TMO])) break; if (_sp > XB_SPIN_CAP) { atomicAdd(&(bar)[XB_TMO], 1u); break; } } } } while (0)
; __device__ __forceinline__ void xcd_barrier(const XcdBarrier& b) {
;     ...
;             __builtin_amdgcn_fence(__ATOMIC_RELEASE, "agent");
;             asm volatile("s_waitcnt vmcnt(0)" ::: "memory");
;             const unsigned og = xb_add(&bar[XB_TOP], 1u);
;             const unsigned tg = og / nx;
;             if (og + 1u == (tg + 1u) * nx) xb_add(&bar[XB_TOPGEN], 1u);
;             else XB_SPIN(xb_ld(&bar[XB_TOPGEN]) == tg, bar);
;             __builtin_amdgcn_fence(__ATOMIC_ACQUIRE, "agent");
;             xb_add(&bar[XB_XGEN(b.x)], 1u);
;             asm volatile("s_waitcnt vmcnt(0)" ::: "memory");
.LBB0_571:
	s_or_b64 exec, exec, s[12:13]
	s_waitcnt vmcnt(0)
	global_atomic_add v[166:167], v190, off
	s_waitcnt vmcnt(0)

; __device__ __forceinline__ unsigned xb_ld(unsigned* p)              { return __hip_atomic_load(p, __ATOMIC_RELAXED, __HIP_MEMORY_SCOPE_AGENT); }
; __device__ __forceinline__ unsigned xb_add(unsigned* p, unsigned v) { return __hip_atomic_fetch_add(p, v, __ATOMIC_RELAXED, __HIP_MEMORY_SCOPE_AGENT); }
; #define XB_SPIN(cond, bar) do { unsigned _sp = 0; while (cond) { __builtin_amdgcn_s_sleep(1); \
;     if ((++_sp & 255u) == 0u) { if (xb_ld(&(bar)[XB_TMO])) break; if (_sp > XB_SPIN_CAP) { atomicAdd(&(bar)[XB_TMO], 1u); break; } } } } while (0)
; __device__ __forceinline__ void xcd_barrier(const XcdBarrier& b) {
;     ...
;         const unsigned old = xb_add(&bar[XB_XSUB(b.x)], 1u);
;         const unsigned gen = old / nloc;
;         if (old + 1u == (gen + 1u) * nloc) {
;             __builtin_amdgcn_fence(__ATOMIC_RELEASE, "agent");
;             asm volatile("s_waitcnt vmcnt(0)" ::: "memory");
;             const unsigned og = xb_add(&bar[XB_TOP], 1u);
;             const unsigned tg = og / nx;
;             if (og + 1u == (tg + 1u) * nx) xb_add(&bar[XB_TOPGEN], 1u);
;             else XB_SPIN(xb_ld(&bar[XB_TOPGEN]) == tg, bar);
;             __builtin_amdgcn_fence(__ATOMIC_ACQUIRE, "agent");
;             xb_add(&bar[XB_XGEN(b.x)], 1u);
;             asm volatile("s_waitcnt vmcnt(0)" ::: "memory");
;         } else {
;             XB_SPIN(xb_ld(&bar[XB_XGEN(b.x)]) == gen, bar);
.LBB0_652:
	global_atomic_add v3, v[164:165], v190, off sc0
	buffer_inv sc1
	v_cvt_f32_u32_e32 v1, v2
	v_sub_u32_e32 v4, 0, v2
	v_rcp_iflag_f32_e32 v1, v1
	s_nop 0
	v_mul_f32_e32 v1, 0x4f7ffffe, v1
	v_cvt_u32_f32_e32 v1, v1
	v_mul_lo_u32 v4, v4, v1
	v_mul_hi_u32 v4, v1, v4
	v_add_u32_e32 v1, v1, v4
	s_waitcnt vmcnt(0)
	v_mul_hi_u32 v1, v3, v1
	v_mul_lo_u32 v4, v1, v2
	v_sub_u32_e32 v4, v3, v4
	v_add_u32_e32 v5, 1, v1
	v_cmp_ge_u32_e32 vcc, v4, v2
	v_add_u32_e32 v3, 1, v3
	s_nop 0
	v_cndmask_b32_e32 v1, v1, v5, vcc
	v_sub_u32_e32 v5, v4, v2
	v_cndmask_b32_e32 v4, v4, v5, vcc
	v_add_u32_e32 v5, 1, v1
	v_cmp_ge_u32_e32 vcc, v4, v2
	s_nop 1
	v_cndmask_b32_e32 v1, v1, v5, vcc
	v_mul_lo_u32 v4, v2, v1
	v_add_u32_e32 v2, v4, v2
	v_cmp_ne_u32_e32 vcc, v3, v2
	s_and_saveexec_b64 s[6:7], vcc
	s_xor_b64 s[6:7], exec, s[6:7]
	s_cbranch_execz .LBB0_666
	s_waitcnt lgkmcnt(0)
	global_load_dword v0, v[166:167], off sc1
	s_waitcnt vmcnt(0)
	v_cmp_eq_u32_e32 vcc, v0, v1
	s_and_saveexec_b64 s[12:13], vcc
	s_cbranch_execz .LBB0_665
	s_mov_b32 s8, 1
	s_mov_b64 s[38:39], 0
	s_branch .LBB0_656

; __device__ __forceinline__ unsigned xb_ld(unsigned* p)              { return __hip_atomic_load(p, __ATOMIC_RELAXED, __HIP_MEMORY_SCOPE_AGENT); }
; #define XB_SPIN(cond, bar) do { unsigned _sp = 0; while (cond) { __builtin_amdgcn_s_sleep(1); \
;     if ((++_sp & 255u) == 0u) { if (xb_ld(&(bar)[XB_TMO])) break; if (_sp > XB_SPIN_CAP) { atomicAdd(&(bar)[XB_TMO], 1u); break; } } } } while (0)
; __device__ __forceinline__ void xcd_barrier(const XcdBarrier& b) {
;     ...
;             XB_SPIN(xb_ld(&bar[XB_XGEN(b.x)]) == gen, bar);
;             __builtin_amdgcn_fence(__ATOMIC_ACQUIRE, "agent");
;             asm volatile("s_waitcnt vmcnt(0)" ::: "memory");
;         }
.LBB0_665:
	s_or_b64 exec, exec, s[12:13]
	s_waitcnt vmcnt(0)
	s_waitcnt vmcnt(0)

; __device__ __forceinline__ unsigned xb_ld(unsigned* p)              { return __hip_atomic_load(p, __ATOMIC_RELAXED, __HIP_MEMORY_SCOPE_AGENT); }
; __device__ __forceinline__ unsigned xb_add(unsigned* p, unsigned v) { return __hip_atomic_fetch_add(p, v, __ATOMIC_RELAXED, __HIP_MEMORY_SCOPE_AGENT); }
; #define XB_SPIN(cond, bar) do { unsigned _sp = 0; while (cond) { __builtin_amdgcn_s_sleep(1); \
;     if ((++_sp & 255u) == 0u) { if (xb_ld(&(bar)[XB_TMO])) break; if (_sp > XB_SPIN_CAP) { atomicAdd(&(bar)[XB_TMO], 1u); break; } } } } while (0)
; __device__ __forceinline__ void xcd_barrier(const XcdBarrier& b) {
;     ...
;             __builtin_amdgcn_fence(__ATOMIC_RELEASE, "agent");
;             asm volatile("s_waitcnt vmcnt(0)" ::: "memory");
;             const unsigned og = xb_add(&bar[XB_TOP], 1u);
;             const unsigned tg = og / nx;
;             if (og + 1u == (tg + 1u) * nx) xb_add(&bar[XB_TOPGEN], 1u);
;             else XB_SPIN(xb_ld(&bar[XB_TOPGEN]) == tg, bar);
;             __builtin_amdgcn_fence(__ATOMIC_ACQUIRE, "agent");
;             xb_add(&bar[XB_XGEN(b.x)], 1u);
;             asm volatile("s_waitcnt vmcnt(0)" ::: "memory");
.LBB0_932:
	s_or_b64 exec, exec, s[6:7]
	s_waitcnt vmcnt(0)
	global_atomic_add v[166:167], v190, off
	s_waitcnt vmcnt(0)
